# v23 + hand-written Ymat Toeplitz phase: constant per-lane offsets, scalar bases, ring of 4 iterations in flight, no divergent branches
# speedup vs baseline: 1.0248x; 1.0046x over previous
; __device__ void phase_ymat_toeplitz(PP P, int wid) {
;     ...
;     for (size_t it = (size_t)blockIdx.x * NTHREADS + tidx; it < total; it += (size_t)gridDim.x * NTHREADS) {
;         const int k8 = (int)(it & 63) * 8, n = (int)(it >> 6) & 511, jg = (int)(it >> 15);
;         const int t = n >> 4, i = n & 15, s = k8 >> 4, j0 = k8 & 15;
;         const float* kf = ktab + ((size_t)jg * 2 + 0) * 32 * 256, *kb = ktab + ((size_t)jg * 2 + 1) * 32 * 256;
;         float f[8];
;         if (s < t) { load8f(kf + (t - s) * 256 + i * 16 + j0, f); }
;         else if (s > t) { load8f(kb + (s - t) * 256 + i * 16 + j0, f); }
;         else { float a[8], b[8]; load8f(kf + i * 16 + j0, a); load8f(kb + i * 16 + j0, b);
;             const int j = jg >> 6, g = jg & 63; const float dsk = P->in[21][j * D + g * 16 + i];
; #pragma unroll
;             for (int q = 0; q < 8; ++q) f[q] = a[q] + b[q] + ((j0 + q) == i ? dsk : 0.f); }
;         *(u32x4*)((bf16_t*)(P->ws + WS_YMAT) + ((size_t)jg * 512 + n) * XLD + k8) = pack8(f);
;     }
.LBB0_96:
	s_or_b64 exec, exec, s[4:5]
	v_readlane_b32 s80, v255, 0
	v_readlane_b32 s81, v255, 1
	s_mov_b64 s[4:5], s[80:81]
	s_barrier
	v_mbcnt_lo_u32_b32 v0, -1, 0
	v_mbcnt_hi_u32_b32 v0, -1, v0
	s_load_dwordx2 s[6:7], s[4:5], 0xe0
	v_add_u32_e32 v2, s82, v0
	s_mov_b32 s3, 0
	s_lshl_b64 s[8:9], s[2:3], 9
	v_ashrrev_i32_e32 v3, 31, v2
	v_lshl_add_u64 v[8:9], s[8:9], 0, v[2:3]
	s_mov_b64 s[0:1], 0x400000
	v_cmp_gt_u64_e32 vcc, s[0:1], v[8:9]
	s_and_saveexec_b64 s[10:11], vcc
	s_cbranch_execz .LBB0_107
	s_cmp_lg_u32 s14, 0x100
	s_cbranch_scc1 .Ltp_orig
	s_load_dwordx2 s[30:31], s[4:5], 0xa8
	v_mbcnt_lo_u32_b32 v0, -1, 0
	v_mbcnt_hi_u32_b32 v0, -1, v0
	s_lshr_b32 s0, s82, 6
	s_lshl_b32 s1, s2, 3
	s_add_i32 s0, s1, s0
	s_and_b32 s1, s0, 0x1ff
	s_lshr_b32 s20, s2, 6
	s_lshr_b32 s21, s1, 4
	s_and_b32 s22, s1, 15
	v_lshrrev_b32_e32 v1, 1, v0
	v_and_b32_e32 v8, 1, v0
	v_lshlrev_b32_e32 v2, 5, v8
	v_lshlrev_b32_e32 v8, 3, v8
	s_lshl_b32 s23, s22, 6
	v_add_u32_e32 v2, s23, v2
	v_sub_u32_e32 v3, s21, v1
	v_subrev_u32_e32 v4, s21, v1
	v_cmp_ge_u32_e32 vcc, s21, v1
	v_lshl_add_u32 v5, v3, 10, v2
	v_lshl_add_u32 v6, v4, 10, v2
	v_add_u32_e32 v6, 0x8000, v6
	v_add_u32_e32 v7, 0x8000, v2
	v_cmp_eq_u32_e64 s[24:25], s21, v1
	v_cndmask_b32_e32 v5, v6, v5, vcc
	v_lshlrev_b32_e32 v10, 4, v0
	v_mov_b32_e32 v11, 0
	v_add_u32_e32 v9, 0, v8
	v_cmp_eq_u32_e32 vcc, s22, v9
	s_nop 1
	v_cndmask_b32_e64 v12, 0, 1.0, vcc
	v_add_u32_e32 v9, 1, v8
	v_cmp_eq_u32_e32 vcc, s22, v9
	s_nop 1
	v_cndmask_b32_e64 v13, 0, 1.0, vcc
	v_add_u32_e32 v9, 2, v8
	v_cmp_eq_u32_e32 vcc, s22, v9
	s_nop 1
	v_cndmask_b32_e64 v14, 0, 1.0, vcc
	v_add_u32_e32 v9, 3, v8
	v_cmp_eq_u32_e32 vcc, s22, v9
	s_nop 1
	v_cndmask_b32_e64 v15, 0, 1.0, vcc
	v_add_u32_e32 v9, 4, v8
	v_cmp_eq_u32_e32 vcc, s22, v9
	s_nop 1
	v_cndmask_b32_e64 v16, 0, 1.0, vcc
	v_add_u32_e32 v9, 5, v8
	v_cmp_eq_u32_e32 vcc, s22, v9
	s_nop 1
	v_cndmask_b32_e64 v17, 0, 1.0, vcc
	v_add_u32_e32 v9, 6, v8
	v_cmp_eq_u32_e32 vcc, s22, v9
	s_nop 1
	v_cndmask_b32_e64 v18, 0, 1.0, vcc
	v_add_u32_e32 v9, 7, v8
	v_cmp_eq_u32_e32 vcc, s22, v9
	s_nop 1
	v_cndmask_b32_e64 v19, 0, 1.0, vcc
	s_waitcnt lgkmcnt(0)
	s_lshl_b32 s0, s20, 16
	s_add_u32 s16, s6, 0x9800000
	s_addc_u32 s17, s7, 0
	s_add_u32 s16, s16, s0
	s_addc_u32 s17, s17, 0
	s_mul_i32 s0, s20, 0xc0000
	s_mul_i32 s1, s1, 0x600
	s_add_i32 s0, s0, s1
	s_add_u32 s18, s6, 0x3800000
	s_addc_u32 s19, s7, 0
	s_add_u32 s18, s18, s0
	s_addc_u32 s19, s19, 0
	s_lshl_b32 s0, s20, 4
	s_add_i32 s0, s0, s22
	s_lshl_b32 s0, s0, 2
	s_add_u32 s30, s30, s0
	s_addc_u32 s31, s31, 0
	s_mov_b32 s13, 0
	s_mul_i32 s0, s13, 0x40000
	s_add_u32 s26, s16, s0
	s_addc_u32 s27, s17, 0
	s_lshl_b32 s0, s13, 8
	s_add_u32 s28, s30, s0
	s_addc_u32 s29, s31, 0
	global_load_dwordx4 v[24:27], v5, s[26:27]
	global_load_dwordx4 v[28:31], v5, s[26:27] offset:16
	s_mov_b64 exec, s[24:25]
	global_load_dwordx4 v[32:35], v7, s[26:27]
	global_load_dwordx4 v[36:39], v7, s[26:27] offset:16
	global_load_dword v40, v11, s[28:29]
	s_mov_b64 exec, -1
	s_mov_b32 s23, 1
	s_mul_i32 s0, s23, 0x40000
	s_add_u32 s26, s16, s0
	s_addc_u32 s27, s17, 0
	s_lshl_b32 s0, s23, 8
	s_add_u32 s28, s30, s0
	s_addc_u32 s29, s31, 0
	global_load_dwordx4 v[42:45], v5, s[26:27]
	global_load_dwordx4 v[46:49], v5, s[26:27] offset:16
	s_mov_b64 exec, s[24:25]
	global_load_dwordx4 v[50:53], v7, s[26:27]
	global_load_dwordx4 v[54:57], v7, s[26:27] offset:16
	global_load_dword v58, v11, s[28:29]
	s_mov_b64 exec, -1
	s_mov_b32 s23, 2
	s_mul_i32 s0, s23, 0x40000
	s_add_u32 s26, s16, s0
	s_addc_u32 s27, s17, 0
	s_lshl_b32 s0, s23, 8
	s_add_u32 s28, s30, s0
	s_addc_u32 s29, s31, 0
	global_load_dwordx4 v[60:63], v5, s[26:27]
	global_load_dwordx4 v[64:67], v5, s[26:27] offset:16
	s_mov_b64 exec, s[24:25]
	global_load_dwordx4 v[68:71], v7, s[26:27]
	global_load_dwordx4 v[72:75], v7, s[26:27] offset:16
	global_load_dword v76, v11, s[28:29]
	s_mov_b64 exec, -1
	s_mov_b32 s23, 3
	s_mul_i32 s0, s23, 0x40000
	s_add_u32 s26, s16, s0
	s_addc_u32 s27, s17, 0
	s_lshl_b32 s0, s23, 8
	s_add_u32 s28, s30, s0
	s_addc_u32 s29, s31, 0
	global_load_dwordx4 v[78:81], v5, s[26:27]
	global_load_dwordx4 v[82:85], v5, s[26:27] offset:16
	s_mov_b64 exec, s[24:25]
	global_load_dwordx4 v[86:89], v7, s[26:27]
	global_load_dwordx4 v[90:93], v7, s[26:27] offset:16
	global_load_dword v94, v11, s[28:29]
	s_mov_b64 exec, -1
	s_waitcnt vmcnt(15)
	s_mov_b64 exec, s[24:25]
	v_pk_add_f32 v[24:25], v[24:25], v[32:33]
	v_pk_add_f32 v[26:27], v[26:27], v[34:35]
	v_pk_add_f32 v[28:29], v[28:29], v[36:37]
	v_pk_add_f32 v[30:31], v[30:31], v[38:39]
	v_pk_fma_f32 v[24:25], v[12:13], v[40:41], v[24:25] op_sel_hi:[1,0,1]
	v_pk_fma_f32 v[26:27], v[14:15], v[40:41], v[26:27] op_sel_hi:[1,0,1]
	v_pk_fma_f32 v[28:29], v[16:17], v[40:41], v[28:29] op_sel_hi:[1,0,1]
	v_pk_fma_f32 v[30:31], v[18:19], v[40:41], v[30:31] op_sel_hi:[1,0,1]
	s_mov_b64 exec, -1
	s_nop 0
	v_cvt_pk_bf16_f32 v20, v24, v25
	v_cvt_pk_bf16_f32 v21, v26, v27
	v_cvt_pk_bf16_f32 v22, v28, v29
	v_cvt_pk_bf16_f32 v23, v30, v31
	s_mul_i32 s0, s13, 0x300000
	s_add_u32 s26, s18, s0
	s_addc_u32 s27, s19, 0
	global_store_dwordx4 v10, v[20:23], s[26:27]
	s_add_i32 s23, s13, 4
	s_cmp_lt_u32 s23, 32
	s_cselect_b32 s23, s23, s13
	s_mul_i32 s0, s23, 0x40000
	s_add_u32 s26, s16, s0
	s_addc_u32 s27, s17, 0
	s_lshl_b32 s0, s23, 8
	s_add_u32 s28, s30, s0
	s_addc_u32 s29, s31, 0
	global_load_dwordx4 v[24:27], v5, s[26:27]
	global_load_dwordx4 v[28:31], v5, s[26:27] offset:16
	s_mov_b64 exec, s[24:25]
	global_load_dwordx4 v[32:35], v7, s[26:27]
	global_load_dwordx4 v[36:39], v7, s[26:27] offset:16
	global_load_dword v40, v11, s[28:29]
	s_mov_b64 exec, -1
	s_add_i32 s21, s13, 1
	s_waitcnt vmcnt(16)
; __device__ void phase_ymat_toeplitz(PP P, int wid) {
;     ...
;     for (size_t it = (size_t)blockIdx.x * NTHREADS + tidx; it < total; it += (size_t)gridDim.x * NTHREADS) {
;         const int k8 = (int)(it & 63) * 8, n = (int)(it >> 6) & 511, jg = (int)(it >> 15);
;         const int t = n >> 4, i = n & 15, s = k8 >> 4, j0 = k8 & 15;
;         const float* kf = ktab + ((size_t)jg * 2 + 0) * 32 * 256, *kb = ktab + ((size_t)jg * 2 + 1) * 32 * 256;
;         float f[8];
;         if (s < t) { load8f(kf + (t - s) * 256 + i * 16 + j0, f); }
;         else if (s > t) { load8f(kb + (s - t) * 256 + i * 16 + j0, f); }
;         else { float a[8], b[8]; load8f(kf + i * 16 + j0, a); load8f(kb + i * 16 + j0, b);
;             const int j = jg >> 6, g = jg & 63; const float dsk = P->in[21][j * D + g * 16 + i];
; #pragma unroll
;             for (int q = 0; q < 8; ++q) f[q] = a[q] + b[q] + ((j0 + q) == i ? dsk : 0.f); }
;         *(u32x4*)((bf16_t*)(P->ws + WS_YMAT) + ((size_t)jg * 512 + n) * XLD + k8) = pack8(f);
;     }
	s_mov_b64 exec, s[24:25]
	v_pk_add_f32 v[42:43], v[42:43], v[50:51]
	v_pk_add_f32 v[44:45], v[44:45], v[52:53]
	v_pk_add_f32 v[46:47], v[46:47], v[54:55]
	v_pk_add_f32 v[48:49], v[48:49], v[56:57]
	v_pk_fma_f32 v[42:43], v[12:13], v[58:59], v[42:43] op_sel_hi:[1,0,1]
	v_pk_fma_f32 v[44:45], v[14:15], v[58:59], v[44:45] op_sel_hi:[1,0,1]
	v_pk_fma_f32 v[46:47], v[16:17], v[58:59], v[46:47] op_sel_hi:[1,0,1]
	v_pk_fma_f32 v[48:49], v[18:19], v[58:59], v[48:49] op_sel_hi:[1,0,1]
	s_mov_b64 exec, -1
	s_nop 0
	v_cvt_pk_bf16_f32 v20, v42, v43
	v_cvt_pk_bf16_f32 v21, v44, v45
	v_cvt_pk_bf16_f32 v22, v46, v47
	v_cvt_pk_bf16_f32 v23, v48, v49
	s_mul_i32 s0, s21, 0x300000
	s_add_u32 s26, s18, s0
	s_addc_u32 s27, s19, 0
	global_store_dwordx4 v10, v[20:23], s[26:27]
	s_add_i32 s23, s21, 4
	s_cmp_lt_u32 s23, 32
	s_cselect_b32 s23, s23, s21
	s_mul_i32 s0, s23, 0x40000
	s_add_u32 s26, s16, s0
	s_addc_u32 s27, s17, 0
	s_lshl_b32 s0, s23, 8
	s_add_u32 s28, s30, s0
	s_addc_u32 s29, s31, 0
	global_load_dwordx4 v[42:45], v5, s[26:27]
	global_load_dwordx4 v[46:49], v5, s[26:27] offset:16
	s_mov_b64 exec, s[24:25]
	global_load_dwordx4 v[50:53], v7, s[26:27]
	global_load_dwordx4 v[54:57], v7, s[26:27] offset:16
	global_load_dword v58, v11, s[28:29]
	s_mov_b64 exec, -1
	s_add_i32 s21, s13, 2
	s_waitcnt vmcnt(17)
	s_mov_b64 exec, s[24:25]
	v_pk_add_f32 v[60:61], v[60:61], v[68:69]
	v_pk_add_f32 v[62:63], v[62:63], v[70:71]
	v_pk_add_f32 v[64:65], v[64:65], v[72:73]
	v_pk_add_f32 v[66:67], v[66:67], v[74:75]
	v_pk_fma_f32 v[60:61], v[12:13], v[76:77], v[60:61] op_sel_hi:[1,0,1]
	v_pk_fma_f32 v[62:63], v[14:15], v[76:77], v[62:63] op_sel_hi:[1,0,1]
	v_pk_fma_f32 v[64:65], v[16:17], v[76:77], v[64:65] op_sel_hi:[1,0,1]
	v_pk_fma_f32 v[66:67], v[18:19], v[76:77], v[66:67] op_sel_hi:[1,0,1]
	s_mov_b64 exec, -1
	s_nop 0
	v_cvt_pk_bf16_f32 v20, v60, v61
	v_cvt_pk_bf16_f32 v21, v62, v63
	v_cvt_pk_bf16_f32 v22, v64, v65
	v_cvt_pk_bf16_f32 v23, v66, v67
	s_mul_i32 s0, s21, 0x300000
	s_add_u32 s26, s18, s0
	s_addc_u32 s27, s19, 0
	global_store_dwordx4 v10, v[20:23], s[26:27]
	s_add_i32 s23, s21, 4
	s_cmp_lt_u32 s23, 32
	s_cselect_b32 s23, s23, s21
	s_mul_i32 s0, s23, 0x40000
	s_add_u32 s26, s16, s0
	s_addc_u32 s27, s17, 0
	s_lshl_b32 s0, s23, 8
	s_add_u32 s28, s30, s0
	s_addc_u32 s29, s31, 0
	global_load_dwordx4 v[60:63], v5, s[26:27]
	global_load_dwordx4 v[64:67], v5, s[26:27] offset:16
	s_mov_b64 exec, s[24:25]
	global_load_dwordx4 v[68:71], v7, s[26:27]
	global_load_dwordx4 v[72:75], v7, s[26:27] offset:16
	global_load_dword v76, v11, s[28:29]
	s_mov_b64 exec, -1
	s_add_i32 s21, s13, 3
	s_waitcnt vmcnt(18)
	s_mov_b64 exec, s[24:25]
	v_pk_add_f32 v[78:79], v[78:79], v[86:87]
	v_pk_add_f32 v[80:81], v[80:81], v[88:89]
	v_pk_add_f32 v[82:83], v[82:83], v[90:91]
	v_pk_add_f32 v[84:85], v[84:85], v[92:93]
	v_pk_fma_f32 v[78:79], v[12:13], v[94:95], v[78:79] op_sel_hi:[1,0,1]
	v_pk_fma_f32 v[80:81], v[14:15], v[94:95], v[80:81] op_sel_hi:[1,0,1]
	v_pk_fma_f32 v[82:83], v[16:17], v[94:95], v[82:83] op_sel_hi:[1,0,1]
	v_pk_fma_f32 v[84:85], v[18:19], v[94:95], v[84:85] op_sel_hi:[1,0,1]
	s_mov_b64 exec, -1
	s_nop 0
	v_cvt_pk_bf16_f32 v20, v78, v79
	v_cvt_pk_bf16_f32 v21, v80, v81
	v_cvt_pk_bf16_f32 v22, v82, v83
	v_cvt_pk_bf16_f32 v23, v84, v85
	s_mul_i32 s0, s21, 0x300000
	s_add_u32 s26, s18, s0
	s_addc_u32 s27, s19, 0
	global_store_dwordx4 v10, v[20:23], s[26:27]
	s_add_i32 s23, s21, 4
	s_cmp_lt_u32 s23, 32
	s_cselect_b32 s23, s23, s21
	s_mul_i32 s0, s23, 0x40000
	s_add_u32 s26, s16, s0
	s_addc_u32 s27, s17, 0
	s_lshl_b32 s0, s23, 8
	s_add_u32 s28, s30, s0
	s_addc_u32 s29, s31, 0
	global_load_dwordx4 v[78:81], v5, s[26:27]
	global_load_dwordx4 v[82:85], v5, s[26:27] offset:16
	s_mov_b64 exec, s[24:25]
	global_load_dwordx4 v[86:89], v7, s[26:27]
	global_load_dwordx4 v[90:93], v7, s[26:27] offset:16
	global_load_dword v94, v11, s[28:29]
	s_mov_b64 exec, -1
	s_mov_b32 s13, 4
; __device__ void phase_ymat_toeplitz(PP P, int wid) {
;     ...
;     for (size_t it = (size_t)blockIdx.x * NTHREADS + tidx; it < total; it += (size_t)gridDim.x * NTHREADS) {
;         const int k8 = (int)(it & 63) * 8, n = (int)(it >> 6) & 511, jg = (int)(it >> 15);
;         const int t = n >> 4, i = n & 15, s = k8 >> 4, j0 = k8 & 15;
;         const float* kf = ktab + ((size_t)jg * 2 + 0) * 32 * 256, *kb = ktab + ((size_t)jg * 2 + 1) * 32 * 256;
;         float f[8];
;         if (s < t) { load8f(kf + (t - s) * 256 + i * 16 + j0, f); }
;         else if (s > t) { load8f(kb + (s - t) * 256 + i * 16 + j0, f); }
;         else { float a[8], b[8]; load8f(kf + i * 16 + j0, a); load8f(kb + i * 16 + j0, b);
;             const int j = jg >> 6, g = jg & 63; const float dsk = P->in[21][j * D + g * 16 + i];
; #pragma unroll
;             for (int q = 0; q < 8; ++q) f[q] = a[q] + b[q] + ((j0 + q) == i ? dsk : 0.f); }
;         *(u32x4*)((bf16_t*)(P->ws + WS_YMAT) + ((size_t)jg * 512 + n) * XLD + k8) = pack8(f);
;     }
.Ltp_loop:
	s_waitcnt vmcnt(18)
	s_mov_b64 exec, s[24:25]
	v_pk_add_f32 v[24:25], v[24:25], v[32:33]
	v_pk_add_f32 v[26:27], v[26:27], v[34:35]
	v_pk_add_f32 v[28:29], v[28:29], v[36:37]
	v_pk_add_f32 v[30:31], v[30:31], v[38:39]
	v_pk_fma_f32 v[24:25], v[12:13], v[40:41], v[24:25] op_sel_hi:[1,0,1]
	v_pk_fma_f32 v[26:27], v[14:15], v[40:41], v[26:27] op_sel_hi:[1,0,1]
	v_pk_fma_f32 v[28:29], v[16:17], v[40:41], v[28:29] op_sel_hi:[1,0,1]
	v_pk_fma_f32 v[30:31], v[18:19], v[40:41], v[30:31] op_sel_hi:[1,0,1]
	s_mov_b64 exec, -1
	s_nop 0
	v_cvt_pk_bf16_f32 v20, v24, v25
	v_cvt_pk_bf16_f32 v21, v26, v27
	v_cvt_pk_bf16_f32 v22, v28, v29
	v_cvt_pk_bf16_f32 v23, v30, v31
	s_mul_i32 s0, s13, 0x300000
	s_add_u32 s26, s18, s0
	s_addc_u32 s27, s19, 0
	global_store_dwordx4 v10, v[20:23], s[26:27]
	s_add_i32 s23, s13, 4
	s_cmp_lt_u32 s23, 32
	s_cselect_b32 s23, s23, s13
	s_mul_i32 s0, s23, 0x40000
	s_add_u32 s26, s16, s0
	s_addc_u32 s27, s17, 0
	s_lshl_b32 s0, s23, 8
	s_add_u32 s28, s30, s0
	s_addc_u32 s29, s31, 0
	global_load_dwordx4 v[24:27], v5, s[26:27]
	global_load_dwordx4 v[28:31], v5, s[26:27] offset:16
	s_mov_b64 exec, s[24:25]
	global_load_dwordx4 v[32:35], v7, s[26:27]
	global_load_dwordx4 v[36:39], v7, s[26:27] offset:16
	global_load_dword v40, v11, s[28:29]
	s_mov_b64 exec, -1
	s_add_i32 s21, s13, 1
	s_waitcnt vmcnt(18)
	s_mov_b64 exec, s[24:25]
	v_pk_add_f32 v[42:43], v[42:43], v[50:51]
	v_pk_add_f32 v[44:45], v[44:45], v[52:53]
	v_pk_add_f32 v[46:47], v[46:47], v[54:55]
	v_pk_add_f32 v[48:49], v[48:49], v[56:57]
	v_pk_fma_f32 v[42:43], v[12:13], v[58:59], v[42:43] op_sel_hi:[1,0,1]
	v_pk_fma_f32 v[44:45], v[14:15], v[58:59], v[44:45] op_sel_hi:[1,0,1]
	v_pk_fma_f32 v[46:47], v[16:17], v[58:59], v[46:47] op_sel_hi:[1,0,1]
	v_pk_fma_f32 v[48:49], v[18:19], v[58:59], v[48:49] op_sel_hi:[1,0,1]
	s_mov_b64 exec, -1
	s_nop 0
	v_cvt_pk_bf16_f32 v20, v42, v43
	v_cvt_pk_bf16_f32 v21, v44, v45
	v_cvt_pk_bf16_f32 v22, v46, v47
	v_cvt_pk_bf16_f32 v23, v48, v49
	s_mul_i32 s0, s21, 0x300000
	s_add_u32 s26, s18, s0
	s_addc_u32 s27, s19, 0
	global_store_dwordx4 v10, v[20:23], s[26:27]
	s_add_i32 s23, s21, 4
	s_cmp_lt_u32 s23, 32
	s_cselect_b32 s23, s23, s21
	s_mul_i32 s0, s23, 0x40000
	s_add_u32 s26, s16, s0
	s_addc_u32 s27, s17, 0
	s_lshl_b32 s0, s23, 8
	s_add_u32 s28, s30, s0
	s_addc_u32 s29, s31, 0
	global_load_dwordx4 v[42:45], v5, s[26:27]
	global_load_dwordx4 v[46:49], v5, s[26:27] offset:16
	s_mov_b64 exec, s[24:25]
	global_load_dwordx4 v[50:53], v7, s[26:27]
	global_load_dwordx4 v[54:57], v7, s[26:27] offset:16
	global_load_dword v58, v11, s[28:29]
	s_mov_b64 exec, -1
	s_add_i32 s21, s13, 2
	s_waitcnt vmcnt(18)
	s_mov_b64 exec, s[24:25]
	v_pk_add_f32 v[60:61], v[60:61], v[68:69]
	v_pk_add_f32 v[62:63], v[62:63], v[70:71]
	v_pk_add_f32 v[64:65], v[64:65], v[72:73]
	v_pk_add_f32 v[66:67], v[66:67], v[74:75]
	v_pk_fma_f32 v[60:61], v[12:13], v[76:77], v[60:61] op_sel_hi:[1,0,1]
	v_pk_fma_f32 v[62:63], v[14:15], v[76:77], v[62:63] op_sel_hi:[1,0,1]
	v_pk_fma_f32 v[64:65], v[16:17], v[76:77], v[64:65] op_sel_hi:[1,0,1]
	v_pk_fma_f32 v[66:67], v[18:19], v[76:77], v[66:67] op_sel_hi:[1,0,1]
	s_mov_b64 exec, -1
	s_nop 0
	v_cvt_pk_bf16_f32 v20, v60, v61
	v_cvt_pk_bf16_f32 v21, v62, v63
	v_cvt_pk_bf16_f32 v22, v64, v65
	v_cvt_pk_bf16_f32 v23, v66, v67
	s_mul_i32 s0, s21, 0x300000
	s_add_u32 s26, s18, s0
	s_addc_u32 s27, s19, 0
	global_store_dwordx4 v10, v[20:23], s[26:27]
	s_add_i32 s23, s21, 4
	s_cmp_lt_u32 s23, 32
	s_cselect_b32 s23, s23, s21
	s_mul_i32 s0, s23, 0x40000
	s_add_u32 s26, s16, s0
	s_addc_u32 s27, s17, 0
	s_lshl_b32 s0, s23, 8
	s_add_u32 s28, s30, s0
	s_addc_u32 s29, s31, 0
	global_load_dwordx4 v[60:63], v5, s[26:27]
	global_load_dwordx4 v[64:67], v5, s[26:27] offset:16
	s_mov_b64 exec, s[24:25]
	global_load_dwordx4 v[68:71], v7, s[26:27]
	global_load_dwordx4 v[72:75], v7, s[26:27] offset:16
	global_load_dword v76, v11, s[28:29]
	s_mov_b64 exec, -1
	s_add_i32 s21, s13, 3
	s_waitcnt vmcnt(18)
	s_mov_b64 exec, s[24:25]
	v_pk_add_f32 v[78:79], v[78:79], v[86:87]
	v_pk_add_f32 v[80:81], v[80:81], v[88:89]
	v_pk_add_f32 v[82:83], v[82:83], v[90:91]
	v_pk_add_f32 v[84:85], v[84:85], v[92:93]
	v_pk_fma_f32 v[78:79], v[12:13], v[94:95], v[78:79] op_sel_hi:[1,0,1]
	v_pk_fma_f32 v[80:81], v[14:15], v[94:95], v[80:81] op_sel_hi:[1,0,1]
	v_pk_fma_f32 v[82:83], v[16:17], v[94:95], v[82:83] op_sel_hi:[1,0,1]
	v_pk_fma_f32 v[84:85], v[18:19], v[94:95], v[84:85] op_sel_hi:[1,0,1]
	s_mov_b64 exec, -1
	s_nop 0
	v_cvt_pk_bf16_f32 v20, v78, v79
	v_cvt_pk_bf16_f32 v21, v80, v81
	v_cvt_pk_bf16_f32 v22, v82, v83
	v_cvt_pk_bf16_f32 v23, v84, v85
	s_mul_i32 s0, s21, 0x300000
	s_add_u32 s26, s18, s0
	s_addc_u32 s27, s19, 0
	global_store_dwordx4 v10, v[20:23], s[26:27]
	s_add_i32 s23, s21, 4
	s_cmp_lt_u32 s23, 32
	s_cselect_b32 s23, s23, s21
	s_mul_i32 s0, s23, 0x40000
	s_add_u32 s26, s16, s0
	s_addc_u32 s27, s17, 0
	s_lshl_b32 s0, s23, 8
	s_add_u32 s28, s30, s0
	s_addc_u32 s29, s31, 0
	global_load_dwordx4 v[78:81], v5, s[26:27]
	global_load_dwordx4 v[82:85], v5, s[26:27] offset:16
	s_mov_b64 exec, s[24:25]
	global_load_dwordx4 v[86:89], v7, s[26:27]
	global_load_dwordx4 v[90:93], v7, s[26:27] offset:16
	global_load_dword v94, v11, s[28:29]
	s_mov_b64 exec, -1
	s_add_i32 s13, s13, 4
	s_cmp_lt_u32 s13, 32
	s_cbranch_scc1 .Ltp_loop
	s_waitcnt vmcnt(0)
	s_branch .LBB0_107
.Ltp_orig:
	s_waitcnt lgkmcnt(0)
	s_add_u32 s12, s6, 0x9800000
	s_addc_u32 s13, s7, 0
	s_add_u32 s16, s6, 0x3800000
	s_mov_b32 s0, s14
	s_mov_b32 s1, s3
	s_addc_u32 s17, s7, 0
	s_lshl_b64 s[18:19], s[0:1], 9
	s_lshl_b32 s0, s2, 9
	s_add_i32 s0, s82, s0
	v_add_lshl_u32 v18, s0, v0, 3
	s_lshl_b32 s0, s14, 12
	s_mov_b64 s[20:21], 0
	s_mov_b64 s[22:23], 0x8000
	v_mov_b32_e32 v11, 0
	s_movk_i32 s1, 0x600
	s_mov_b64 s[24:25], 0x3fffff
	s_branch .LBB0_99
